# slack work (w_out bf16 copy on type A, gate columns of the adaLN GEMV on type B) now runs before each workgroup's GEMM unit instead of after it, so the phase ends with matrix work only
# speedup vs baseline: 1.0289x; 1.0072x over previous
.Lb_cont:
	s_bitcmp1_b32 s32, 12
	s_cbranch_scc1 .Lb_cont2
	s_or_b32 s32, s32, 0x3000
	s_ashr_i32 s21, s20, 1
	v_and_b32_e32 v178, 63, v0
	s_branch .LBB0_486

.LBB0_485:
	v_mov_b32_e32 v178, v254
	s_barrier
	s_branch .LBB0_493

.LBB0_494:
	s_bitcmp1_b32 s32, 13
	s_cbranch_scc0 .Lnormal494
	s_andn2_b32 s32, s32, 0x2000
	s_and_b32 s66, s2, 7
	s_lshr_b32 s67, s2, 3
	s_mov_b64 s[8:9], -1
	v_and_b32_e32 v254, 63, v0
	s_branch .LBB0_476
